# final rmsnorm fused into the last ffn_down epilogue (f32 rows of out written from the epilogue after the panel exchange); the separate final-norm phase and its barrier are skipped
# baseline (speedup 1.0000x reference)
; __device__ __forceinline__ int opaque_bid() { int t = blockIdx.x; asm volatile("" : "+s"(t)); return t; }
; __global__ void __launch_bounds__(NTHREADS) fwd_megakernel(Params p) {
;     ...
;         else if (ph == NPHASE - 1) phase_rmsnorm<true, true>(XB, p.final_norm, p.out);
;         else {
;             const int l = (ph - 1) / 8, k = (ph - 1) % 8;
;             Sched S; S.G = gridDim.x; S.c = opaque_bid(); S.kind = -1; S.A0 = S.B0 = S.A1 = S.B1 = nullptr; S.O0 = S.O1 = nullptr; S.R0 = nullptr; S.r32 = 0; S.nM = S.nN = 0; S.K = DM;
;             int gK = DM, lda = DM, ldb = DM; int epi = 0;
;             if (k == 0) { if (l > 0) phase_rmsnorm<false, true>(XB, p.norm_mix + (size_t)l * DM, ws + WS_XN); else need_bar = false; }
.Lln_begin:
	s_mov_b64 s[100:101], vcc
	s_and_b32 s0, s90, 7
	s_cmp_eq_u32 s0, 5
	s_cbranch_scc1 .Lln_k4
	s_cmp_lg_u32 s0, 0
	s_cbranch_scc1 .Lln_end
	s_lshr_b32 s1, s90, 3
	s_lshl_b32 s13, s1, 13
	s_lshl_b32 s1, s1, 1
	s_add_i32 s1, s1, -1
	s_mov_b32 s0, 0
	s_branch .Lln_go

; __device__ __forceinline__ float bflo(unsigned w) { return __uint_as_float(w << 16); }
; __device__ __forceinline__ float bfhi(unsigned w) { return __uint_as_float(w & 0xffff0000u); }
; __device__ __forceinline__ unsigned cvt_pk_bf16(float lo, float hi) { unsigned r; asm volatile("v_cvt_pk_bf16_f32 %0, %1, %2" : "=v"(r) : "v"(lo), "v"(hi)); return r; }
;     __device__ __forceinline__ void operator()(const f32x4 (&acc)[2][2][4][2], const Unit& u, int wr, int wc, int fr_in, int fq_in) const {
;     ...
;                 for (int m2 = 0; m2 < 2; ++m2) { const int m = 2 * mh + m2; const size_t off = off0 + (size_t)(ai * HALF + m * 16) * u.ldc;
; #pragma unroll
;                     for (int bj = 0; bj < 2; ++bj) { const f32x4 v0 = acc[ai][bj][m][0] + rv[m2][bj][0], v1 = acc[ai][bj][m][1] + rv[m2][bj][1];
;                         u32x4 w; w.x = cvt_pk_bf16(v0[0], v0[1]); w.y = cvt_pk_bf16(v0[2], v0[3]); w.z = cvt_pk_bf16(v1[0], v1[1]); w.w = cvt_pk_bf16(v1[2], v1[3]);
;                         *(u32x4*)(O + off + bj * HALF) = w; } }
; template <bool OUT_F32, bool IN_BF16>
; __device__ __forceinline__ void phase_rmsnorm(const void* Xv, const float* gain, void* out) {
;     ...
;         for (int r = 0; r < RPT; ++r) { float sq = 0.f;
; #pragma unroll
;             for (int j = 0; j < 4; ++j) { if (IN_BF16) { const u32x4 q = t[r][j]; v[r][j][0] = (f32x4){bflo(q.x), bfhi(q.x), bflo(q.y), bfhi(q.y)}; v[r][j][1] = (f32x4){bflo(q.z), bfhi(q.z), bflo(q.w), bfhi(q.w)}; }
; #pragma unroll
;                 for (int h = 0; h < 2; ++h) { const f32x4 a = v[r][j][h]; sq += (a.x * a.x + a.y * a.y) + (a.z * a.z + a.w * a.w); } }
;             rs[r] = 1.0f / sqrtf(wave_sum(sq) * (1.0f / DM) + EPS); }
.Lln_go:
	v_readlane_b32 s38, v252, 2
	v_readlane_b32 s39, v252, 3
	s_nop 0
	s_sub_u32 s38, s38, 0x90
	s_subb_u32 s39, s39, 0
	s_cmp_eq_u32 s90, 32
	s_cbranch_scc1 .Lln_ka_final
	s_load_dwordx4 s[56:59], s[38:39], 0x38
	s_waitcnt lgkmcnt(0)
	s_cmp_eq_u32 s0, 1
	s_cselect_b32 s56, s58, s56
	s_cselect_b32 s57, s59, s57
	s_add_u32 s56, s56, s13
	s_addc_u32 s57, s57, 0
	s_branch .Lln_ka_done
.Lln_ka_final:
	s_load_dwordx4 s[56:59], s[38:39], 0x70
	s_waitcnt lgkmcnt(0)
	v_writelane_b32 v255, s58, 20
	v_writelane_b32 v255, s59, 21
.Lln_ka_done:
	v_readfirstlane_b32 s58, v174
	v_readfirstlane_b32 s59, v175
	s_add_u32 s64, s88, 0x1b900000
	s_addc_u32 s65, s89, 0
	s_sub_u32 s58, s58, s64
	s_subb_u32 s59, s59, s65
	s_lshr_b32 s13, s58, 20
	s_bfe_u32 s0, s58, 0x30009
	s_lshl_b32 s58, s1, 18
	s_lshl_b32 s59, s13, 13
	s_add_i32 s58, s58, s59
	s_add_u32 s38, s88, 0x30280000
	s_addc_u32 s39, s89, 0
	s_add_u32 s38, s38, s58
	s_addc_u32 s39, s39, 0
	s_lshl_b32 s1, s1, 5
	s_add_i32 s1, s1, s13
	s_lshl_b32 s1, s1, 6
	s_add_u32 s58, s88, 0x40a84000
	s_addc_u32 s59, s89, 0
	s_add_u32 s58, s58, s1
	s_addc_u32 s59, s59, 0
	s_lshl_b32 s1, s0, 10
	s_add_u32 s56, s56, s1
	s_addc_u32 s57, s57, 0
	v_lshrrev_b32_e32 v40, 6, v185
	v_and_b32_e32 v41, 3, v40
	v_lshrrev_b32_e32 v40, 2, v40
	v_bfe_u32 v42, v185, 4, 2
	v_and_b32_e32 v43, 15, v185
	v_lshlrev_b32_e32 v24, 2, v41
	v_lshlrev_b32_e32 v41, 7, v41
	v_lshl_add_u32 v41, v42, 5, v41
	v_lshlrev_b32_e32 v40, 6, v40
	v_add_u32_e32 v40, v40, v43
	v_lshl_add_u32 v35, v40, 4, v24
	v_add_u32_e32 v35, 0x20000, v35
	v_lshlrev_b32_e32 v42, 4, v185
	v_add_u32_e32 v42, 0x20000, v42
	v_and_b32_e32 v3, 63, v185
	v_xor_b32_e32 v2, 16, v3
	v_lshlrev_b32_e32 v2, 2, v2
	v_xor_b32_e32 v3, 32, v3
	v_lshlrev_b32_e32 v3, 2, v3
	v_lshlrev_b32_e32 v43, 5, v185
	s_lshl_b32 s1, s0, 2
	v_add_u32_e32 v32, s1, v43
	v_mov_b32_e32 v33, 1
	global_load_dwordx4 v[88:91], v41, s[56:57]
	global_load_dwordx4 v[80:83], v41, s[56:57] offset:16
	global_load_dwordx4 v[72:75], v41, s[56:57] offset:512
	global_load_dwordx4 v[64:67], v41, s[56:57] offset:528
	v_mov_b32_e32 v104, 0
	v_mov_b32_e32 v105, 0
	v_mov_b32_e32 v106, 0
	v_mov_b32_e32 v107, 0
	v_mov_b32_e32 v96, 0
	v_mov_b32_e32 v97, 0
	v_mov_b32_e32 v98, 0
	v_mov_b32_e32 v99, 0
	v_lshlrev_b32_e32 v120, 16, v124
	v_and_b32_e32 v121, 0xffff0000, v124
	v_lshlrev_b32_e32 v122, 16, v125
	v_and_b32_e32 v123, 0xffff0000, v125
	v_lshlrev_b32_e32 v112, 16, v126
	v_and_b32_e32 v113, 0xffff0000, v126
	v_lshlrev_b32_e32 v114, 16, v127
	v_and_b32_e32 v115, 0xffff0000, v127
	v_fmac_f32_e32 v104, v120, v120
	v_fmac_f32_e32 v104, v121, v121
	v_fmac_f32_e32 v104, v122, v122
	v_fmac_f32_e32 v104, v123, v123
	v_fmac_f32_e32 v104, v112, v112
	v_fmac_f32_e32 v104, v113, v113
	v_fmac_f32_e32 v104, v114, v114
	v_fmac_f32_e32 v104, v115, v115
	v_lshlrev_b32_e32 v120, 16, v92
	v_and_b32_e32 v121, 0xffff0000, v92
	v_lshlrev_b32_e32 v122, 16, v93
	v_and_b32_e32 v123, 0xffff0000, v93
	v_lshlrev_b32_e32 v112, 16, v94
	v_and_b32_e32 v113, 0xffff0000, v94
	v_lshlrev_b32_e32 v114, 16, v95
	v_and_b32_e32 v115, 0xffff0000, v95
	v_fmac_f32_e32 v104, v120, v120
	v_fmac_f32_e32 v104, v121, v121
	v_fmac_f32_e32 v104, v122, v122
	v_fmac_f32_e32 v104, v123, v123
	v_fmac_f32_e32 v104, v112, v112
	v_fmac_f32_e32 v104, v113, v113
	v_fmac_f32_e32 v104, v114, v114
	v_fmac_f32_e32 v104, v115, v115
	v_lshlrev_b32_e32 v120, 16, v116
	v_and_b32_e32 v121, 0xffff0000, v116
	v_lshlrev_b32_e32 v122, 16, v117
	v_and_b32_e32 v123, 0xffff0000, v117
	v_lshlrev_b32_e32 v112, 16, v118
	v_and_b32_e32 v113, 0xffff0000, v118
	v_lshlrev_b32_e32 v114, 16, v119
	v_and_b32_e32 v115, 0xffff0000, v119
	v_fmac_f32_e32 v105, v120, v120
	v_fmac_f32_e32 v105, v121, v121
	v_fmac_f32_e32 v105, v122, v122
	v_fmac_f32_e32 v105, v123, v123
	v_fmac_f32_e32 v105, v112, v112
	v_fmac_f32_e32 v105, v113, v113
	v_fmac_f32_e32 v105, v114, v114
	v_fmac_f32_e32 v105, v115, v115
	v_lshlrev_b32_e32 v120, 16, v84
	v_and_b32_e32 v121, 0xffff0000, v84
	v_lshlrev_b32_e32 v122, 16, v85
	v_and_b32_e32 v123, 0xffff0000, v85
	v_lshlrev_b32_e32 v112, 16, v86
	v_and_b32_e32 v113, 0xffff0000, v86
	v_lshlrev_b32_e32 v114, 16, v87
	v_and_b32_e32 v115, 0xffff0000, v87
	v_fmac_f32_e32 v105, v120, v120
	v_fmac_f32_e32 v105, v121, v121
	v_fmac_f32_e32 v105, v122, v122
	v_fmac_f32_e32 v105, v123, v123
	v_fmac_f32_e32 v105, v112, v112
	v_fmac_f32_e32 v105, v113, v113
	v_fmac_f32_e32 v105, v114, v114
	v_fmac_f32_e32 v105, v115, v115
	v_lshlrev_b32_e32 v120, 16, v108
	v_and_b32_e32 v121, 0xffff0000, v108
	v_lshlrev_b32_e32 v122, 16, v109
	v_and_b32_e32 v123, 0xffff0000, v109
	v_lshlrev_b32_e32 v112, 16, v110
	v_and_b32_e32 v113, 0xffff0000, v110
	v_lshlrev_b32_e32 v114, 16, v111
	v_and_b32_e32 v115, 0xffff0000, v111
	v_fmac_f32_e32 v106, v120, v120
	v_fmac_f32_e32 v106, v121, v121
	v_fmac_f32_e32 v106, v122, v122
	v_fmac_f32_e32 v106, v123, v123
	v_fmac_f32_e32 v106, v112, v112
	v_fmac_f32_e32 v106, v113, v113
	v_fmac_f32_e32 v106, v114, v114
	v_fmac_f32_e32 v106, v115, v115
	v_lshlrev_b32_e32 v120, 16, v76
	v_and_b32_e32 v121, 0xffff0000, v76
	v_lshlrev_b32_e32 v122, 16, v77
	v_and_b32_e32 v123, 0xffff0000, v77
	v_lshlrev_b32_e32 v112, 16, v78
	v_and_b32_e32 v113, 0xffff0000, v78
	v_lshlrev_b32_e32 v114, 16, v79
	v_and_b32_e32 v115, 0xffff0000, v79
	v_fmac_f32_e32 v106, v120, v120
	v_fmac_f32_e32 v106, v121, v121
	v_fmac_f32_e32 v106, v122, v122
	v_fmac_f32_e32 v106, v123, v123
	v_fmac_f32_e32 v106, v112, v112
	v_fmac_f32_e32 v106, v113, v113
	v_fmac_f32_e32 v106, v114, v114
	v_fmac_f32_e32 v106, v115, v115
	v_lshlrev_b32_e32 v120, 16, v100
	v_and_b32_e32 v121, 0xffff0000, v100
	v_lshlrev_b32_e32 v122, 16, v101
; __device__ __forceinline__ float bflo(unsigned w) { return __uint_as_float(w << 16); }
; __device__ __forceinline__ float bfhi(unsigned w) { return __uint_as_float(w & 0xffff0000u); }
; __device__ __forceinline__ float wave_sum(float v) {
; #pragma unroll
;     for (int o = 1; o < 64; o <<= 1) v += __shfl_xor(v, o);
;     return v;
; template <bool OUT_F32, bool IN_BF16>
; __device__ __forceinline__ void phase_rmsnorm(const void* Xv, const float* gain, void* out) {
;     ...
;         for (int r = 0; r < RPT; ++r) { float sq = 0.f;
; #pragma unroll
;             for (int j = 0; j < 4; ++j) { if (IN_BF16) { const u32x4 q = t[r][j]; v[r][j][0] = (f32x4){bflo(q.x), bfhi(q.x), bflo(q.y), bfhi(q.y)}; v[r][j][1] = (f32x4){bflo(q.z), bfhi(q.z), bflo(q.w), bfhi(q.w)}; }
; #pragma unroll
;                 for (int h = 0; h < 2; ++h) { const f32x4 a = v[r][j][h]; sq += (a.x * a.x + a.y * a.y) + (a.z * a.z + a.w * a.w); } }
;             rs[r] = 1.0f / sqrtf(wave_sum(sq) * (1.0f / DM) + EPS); }
	v_and_b32_e32 v123, 0xffff0000, v101
	v_lshlrev_b32_e32 v112, 16, v102
	v_and_b32_e32 v113, 0xffff0000, v102
	v_lshlrev_b32_e32 v114, 16, v103
	v_and_b32_e32 v115, 0xffff0000, v103
	v_fmac_f32_e32 v107, v120, v120
	v_fmac_f32_e32 v107, v121, v121
	v_fmac_f32_e32 v107, v122, v122
	v_fmac_f32_e32 v107, v123, v123
	v_fmac_f32_e32 v107, v112, v112
	v_fmac_f32_e32 v107, v113, v113
	v_fmac_f32_e32 v107, v114, v114
	v_fmac_f32_e32 v107, v115, v115
	v_lshlrev_b32_e32 v120, 16, v68
	v_and_b32_e32 v121, 0xffff0000, v68
	v_lshlrev_b32_e32 v122, 16, v69
	v_and_b32_e32 v123, 0xffff0000, v69
	v_lshlrev_b32_e32 v112, 16, v70
	v_and_b32_e32 v113, 0xffff0000, v70
	v_lshlrev_b32_e32 v114, 16, v71
	v_and_b32_e32 v115, 0xffff0000, v71
	v_fmac_f32_e32 v107, v120, v120
	v_fmac_f32_e32 v107, v121, v121
	v_fmac_f32_e32 v107, v122, v122
	v_fmac_f32_e32 v107, v123, v123
	v_fmac_f32_e32 v107, v112, v112
	v_fmac_f32_e32 v107, v113, v113
	v_fmac_f32_e32 v107, v114, v114
	v_fmac_f32_e32 v107, v115, v115
	v_lshlrev_b32_e32 v120, 16, v60
	v_and_b32_e32 v121, 0xffff0000, v60
	v_lshlrev_b32_e32 v122, 16, v61
	v_and_b32_e32 v123, 0xffff0000, v61
	v_lshlrev_b32_e32 v112, 16, v62
	v_and_b32_e32 v113, 0xffff0000, v62
	v_lshlrev_b32_e32 v114, 16, v63
	v_and_b32_e32 v115, 0xffff0000, v63
	v_fmac_f32_e32 v96, v120, v120
	v_fmac_f32_e32 v96, v121, v121
	v_fmac_f32_e32 v96, v122, v122
	v_fmac_f32_e32 v96, v123, v123
	v_fmac_f32_e32 v96, v112, v112
	v_fmac_f32_e32 v96, v113, v113
	v_fmac_f32_e32 v96, v114, v114
	v_fmac_f32_e32 v96, v115, v115
	v_lshlrev_b32_e32 v120, 16, v28
	v_and_b32_e32 v121, 0xffff0000, v28
	v_lshlrev_b32_e32 v122, 16, v29
	v_and_b32_e32 v123, 0xffff0000, v29
	v_lshlrev_b32_e32 v112, 16, v30
	v_and_b32_e32 v113, 0xffff0000, v30
	v_lshlrev_b32_e32 v114, 16, v31
	v_and_b32_e32 v115, 0xffff0000, v31
	v_fmac_f32_e32 v96, v120, v120
	v_fmac_f32_e32 v96, v121, v121
	v_fmac_f32_e32 v96, v122, v122
	v_fmac_f32_e32 v96, v123, v123
	v_fmac_f32_e32 v96, v112, v112
	v_fmac_f32_e32 v96, v113, v113
	v_fmac_f32_e32 v96, v114, v114
	v_fmac_f32_e32 v96, v115, v115
	v_lshlrev_b32_e32 v120, 16, v52
	v_and_b32_e32 v121, 0xffff0000, v52
	v_lshlrev_b32_e32 v122, 16, v53
	v_and_b32_e32 v123, 0xffff0000, v53
	v_lshlrev_b32_e32 v112, 16, v54
	v_and_b32_e32 v113, 0xffff0000, v54
	v_lshlrev_b32_e32 v114, 16, v55
	v_and_b32_e32 v115, 0xffff0000, v55
	v_fmac_f32_e32 v97, v120, v120
	v_fmac_f32_e32 v97, v121, v121
	v_fmac_f32_e32 v97, v122, v122
	v_fmac_f32_e32 v97, v123, v123
	v_fmac_f32_e32 v97, v112, v112
	v_fmac_f32_e32 v97, v113, v113
	v_fmac_f32_e32 v97, v114, v114
	v_fmac_f32_e32 v97, v115, v115
	v_lshlrev_b32_e32 v120, 16, v20
	v_and_b32_e32 v121, 0xffff0000, v20
	v_lshlrev_b32_e32 v122, 16, v21
	v_and_b32_e32 v123, 0xffff0000, v21
	v_lshlrev_b32_e32 v112, 16, v22
	v_and_b32_e32 v113, 0xffff0000, v22
	v_lshlrev_b32_e32 v114, 16, v23
	v_and_b32_e32 v115, 0xffff0000, v23
	v_fmac_f32_e32 v97, v120, v120
	v_fmac_f32_e32 v97, v121, v121
	v_fmac_f32_e32 v97, v122, v122
	v_fmac_f32_e32 v97, v123, v123
	v_fmac_f32_e32 v97, v112, v112
	v_fmac_f32_e32 v97, v113, v113
	v_fmac_f32_e32 v97, v114, v114
	v_fmac_f32_e32 v97, v115, v115
	v_lshlrev_b32_e32 v120, 16, v44
	v_and_b32_e32 v121, 0xffff0000, v44
	v_lshlrev_b32_e32 v122, 16, v45
	v_and_b32_e32 v123, 0xffff0000, v45
	v_lshlrev_b32_e32 v112, 16, v46
	v_and_b32_e32 v113, 0xffff0000, v46
	v_lshlrev_b32_e32 v114, 16, v47
	v_and_b32_e32 v115, 0xffff0000, v47
	v_fmac_f32_e32 v98, v120, v120
	v_fmac_f32_e32 v98, v121, v121
	v_fmac_f32_e32 v98, v122, v122
	v_fmac_f32_e32 v98, v123, v123
	v_fmac_f32_e32 v98, v112, v112
	v_fmac_f32_e32 v98, v113, v113
	v_fmac_f32_e32 v98, v114, v114
	v_fmac_f32_e32 v98, v115, v115
	v_lshlrev_b32_e32 v120, 16, v12
	v_and_b32_e32 v121, 0xffff0000, v12
	v_lshlrev_b32_e32 v122, 16, v13
	v_and_b32_e32 v123, 0xffff0000, v13
	v_lshlrev_b32_e32 v112, 16, v14
	v_and_b32_e32 v113, 0xffff0000, v14
	v_lshlrev_b32_e32 v114, 16, v15
	v_and_b32_e32 v115, 0xffff0000, v15
	v_fmac_f32_e32 v98, v120, v120
	v_fmac_f32_e32 v98, v121, v121
	v_fmac_f32_e32 v98, v122, v122
	v_fmac_f32_e32 v98, v123, v123
	v_fmac_f32_e32 v98, v112, v112
	v_fmac_f32_e32 v98, v113, v113
	v_fmac_f32_e32 v98, v114, v114
	v_fmac_f32_e32 v98, v115, v115
	v_lshlrev_b32_e32 v120, 16, v36
	v_and_b32_e32 v121, 0xffff0000, v36
	v_lshlrev_b32_e32 v122, 16, v37
	v_and_b32_e32 v123, 0xffff0000, v37
	v_lshlrev_b32_e32 v112, 16, v38
	v_and_b32_e32 v113, 0xffff0000, v38
	v_lshlrev_b32_e32 v114, 16, v39
	v_and_b32_e32 v115, 0xffff0000, v39
	v_fmac_f32_e32 v99, v120, v120
	v_fmac_f32_e32 v99, v121, v121
	v_fmac_f32_e32 v99, v122, v122
	v_fmac_f32_e32 v99, v123, v123
	v_fmac_f32_e32 v99, v112, v112
	v_fmac_f32_e32 v99, v113, v113
	v_fmac_f32_e32 v99, v114, v114
	v_fmac_f32_e32 v99, v115, v115
	v_lshlrev_b32_e32 v120, 16, v4
	v_and_b32_e32 v121, 0xffff0000, v4
	v_lshlrev_b32_e32 v122, 16, v5
	v_and_b32_e32 v123, 0xffff0000, v5
	v_lshlrev_b32_e32 v112, 16, v6
	v_and_b32_e32 v113, 0xffff0000, v6
	v_lshlrev_b32_e32 v114, 16, v7
	v_and_b32_e32 v115, 0xffff0000, v7
	v_fmac_f32_e32 v99, v120, v120
	v_fmac_f32_e32 v99, v121, v121
	v_fmac_f32_e32 v99, v122, v122
	v_fmac_f32_e32 v99, v123, v123
	v_fmac_f32_e32 v99, v112, v112
	v_fmac_f32_e32 v99, v113, v113
	v_fmac_f32_e32 v99, v114, v114
	v_fmac_f32_e32 v99, v115, v115
	ds_bpermute_b32 v120, v2, v104
	ds_bpermute_b32 v121, v2, v105
	ds_bpermute_b32 v122, v2, v106
	ds_bpermute_b32 v123, v2, v107
	ds_bpermute_b32 v112, v2, v96
	ds_bpermute_b32 v113, v2, v97
	ds_bpermute_b32 v114, v2, v98
	ds_bpermute_b32 v115, v2, v99
	s_waitcnt lgkmcnt(0)
	v_add_f32_e32 v104, v104, v120
	v_add_f32_e32 v105, v105, v121
	v_add_f32_e32 v106, v106, v122
	v_add_f32_e32 v107, v107, v123
	v_add_f32_e32 v96, v96, v112
	v_add_f32_e32 v97, v97, v113
	v_add_f32_e32 v98, v98, v114
	v_add_f32_e32 v99, v99, v115
	ds_bpermute_b32 v120, v3, v104
	ds_bpermute_b32 v121, v3, v105
	ds_bpermute_b32 v122, v3, v106
	ds_bpermute_b32 v123, v3, v107
	ds_bpermute_b32 v112, v3, v96
	ds_bpermute_b32 v113, v3, v97
	ds_bpermute_b32 v114, v3, v98
	ds_bpermute_b32 v115, v3, v99
	s_waitcnt lgkmcnt(0)
	v_add_f32_e32 v104, v104, v120
	v_add_f32_e32 v105, v105, v121
	v_add_f32_e32 v106, v106, v122
	v_add_f32_e32 v107, v107, v123
	v_add_f32_e32 v96, v96, v112
	v_add_f32_e32 v97, v97, v113
	v_add_f32_e32 v98, v98, v114
	v_add_f32_e32 v99, v99, v115
	v_and_b32_e32 v34, 48, v185
	v_cmp_eq_u32_e32 vcc, 0, v34
	s_and_saveexec_b64 s[64:65], vcc
	ds_write_b32 v35, v104 offset:0
	ds_write_b32 v35, v105 offset:256
	ds_write_b32 v35, v106 offset:512
	ds_write_b32 v35, v107 offset:768
	ds_write_b32 v35, v96 offset:2048
	ds_write_b32 v35, v97 offset:2304
	ds_write_b32 v35, v98 offset:2560
	ds_write_b32 v35, v99 offset:2816
	s_or_b64 exec, exec, s[64:65]
	s_waitcnt lgkmcnt(0)
	s_barrier
; __device__ __forceinline__ float bflo(unsigned w) { return __uint_as_float(w << 16); }
; __device__ __forceinline__ float bfhi(unsigned w) { return __uint_as_float(w & 0xffff0000u); }
; template <bool OUT_F32, bool IN_BF16>
; __device__ __forceinline__ void phase_rmsnorm(const void* Xv, const float* gain, void* out) {
;     ...
;         for (int r = 0; r < RPT; ++r) { float sq = 0.f;
; #pragma unroll
;             for (int j = 0; j < 4; ++j) { if (IN_BF16) { const u32x4 q = t[r][j]; v[r][j][0] = (f32x4){bflo(q.x), bfhi(q.x), bflo(q.y), bfhi(q.y)}; v[r][j][1] = (f32x4){bflo(q.z), bfhi(q.z), bflo(q.w), bfhi(q.w)}; }
; #pragma unroll
;                 for (int h = 0; h < 2; ++h) { const f32x4 a = v[r][j][h]; sq += (a.x * a.x + a.y * a.y) + (a.z * a.z + a.w * a.w); } }
;             rs[r] = 1.0f / sqrtf(wave_sum(sq) * (1.0f / DM) + EPS); }
	v_cmp_gt_u32_e32 vcc, 0x100, v185
	s_and_saveexec_b64 s[64:65], vcc
	s_cbranch_execz .Lln_pub_done
	ds_read_b128 v[16:19], v42
	s_waitcnt lgkmcnt(0)
	v_add_f32_e32 v16, v16, v17
	v_add_f32_e32 v18, v18, v19
	v_add_f32_e32 v34, v16, v18
	global_store_dword v32, v34, s[38:39] sc0 sc1
	s_waitcnt vmcnt(0)

; __device__ __forceinline__ unsigned pk2(float lo, float hi) { const f32x2 v = {lo, hi}; const hwbf16x2 b = __builtin_convertvector(v, hwbf16x2); return __builtin_bit_cast(unsigned, b); }
; template <bool OUT_F32, bool IN_BF16>
; __device__ __forceinline__ void phase_rmsnorm(const void* Xv, const float* gain, void* out) {
;     ...
;             rs[r] = 1.0f / sqrtf(wave_sum(sq) * (1.0f / DM) + EPS); }
; #pragma unroll
;         for (int r = 0; r < RPT; ++r) { const int m = m0 + r * NGW; if (m >= NTOK) continue;
; #pragma unroll
;             for (int j = 0; j < 4; ++j) { const f32x4 y0 = v[r][j][0] * rs[r] * g[j][0], y1 = v[r][j][1] * rs[r] * g[j][1];
;                 if (OUT_F32) { float* o = (float*)out + (size_t)m * DM + 8 * lane + 512 * j; *(f32x4*)o = y0; *(f32x4*)(o + 4) = y1; }
;                 else { u32x4 w; w.x = pk2(y0.x, y0.y); w.y = pk2(y0.z, y0.w); w.z = pk2(y1.x, y1.y); w.w = pk2(y1.z, y1.w); *(u32x4*)((bf16_t*)out + (size_t)m * DM + 8 * lane + 512 * j) = w; } } }
.Lln_rs_done:
	s_or_b64 exec, exec, s[64:65]
	s_waitcnt lgkmcnt(0)
	s_barrier
	v_lshlrev_b32_e32 v2, 2, v40
	v_add_u32_e32 v2, 0x21000, v2
	ds_read_b32 v56, v2 offset:0
	ds_read_b32 v57, v2 offset:64
	ds_read_b32 v58, v2 offset:128
	ds_read_b32 v59, v2 offset:192
	ds_read_b32 v48, v2 offset:512
	ds_read_b32 v49, v2 offset:576
	ds_read_b32 v50, v2 offset:640
	ds_read_b32 v51, v2 offset:704
	s_cmp_eq_u32 s90, 32
	s_cbranch_scc1 .Lln_out_final
	s_mov_b32 s64, 0x4000000
	s_mov_b32 s65, 0
	v_lshl_add_u64 v[0:1], v[174:175], 0, s[64:65]
	s_mov_b32 s64, 0x10000
	s_waitcnt vmcnt(0) lgkmcnt(0)
	v_lshlrev_b32_e32 v120, 16, v124
	v_and_b32_e32 v121, 0xffff0000, v124
	v_lshlrev_b32_e32 v122, 16, v125
	v_and_b32_e32 v123, 0xffff0000, v125
	v_lshlrev_b32_e32 v112, 16, v126
	v_and_b32_e32 v113, 0xffff0000, v126
	v_lshlrev_b32_e32 v114, 16, v127
	v_and_b32_e32 v115, 0xffff0000, v127
	v_mul_f32_e32 v120, v120, v56
	v_mul_f32_e32 v121, v121, v56
	v_mul_f32_e32 v122, v122, v56
	v_mul_f32_e32 v123, v123, v56
	v_mul_f32_e32 v112, v112, v56
	v_mul_f32_e32 v113, v113, v56
	v_mul_f32_e32 v114, v114, v56
	v_mul_f32_e32 v115, v115, v56
	v_pk_mul_f32 v[120:121], v[120:121], v[88:89]
	v_pk_mul_f32 v[122:123], v[122:123], v[90:91]
	v_pk_mul_f32 v[112:113], v[112:113], v[80:81]
	v_pk_mul_f32 v[114:115], v[114:115], v[82:83]
	v_cvt_pk_bf16_f32 v8, v120, v121
	v_cvt_pk_bf16_f32 v9, v122, v123
	v_cvt_pk_bf16_f32 v10, v112, v113
	v_cvt_pk_bf16_f32 v11, v114, v115
	global_store_dwordx4 v[0:1], v[8:11], off
	v_lshlrev_b32_e32 v120, 16, v92
	v_and_b32_e32 v121, 0xffff0000, v92
	v_lshlrev_b32_e32 v122, 16, v93
	v_and_b32_e32 v123, 0xffff0000, v93
	v_lshlrev_b32_e32 v112, 16, v94
	v_and_b32_e32 v113, 0xffff0000, v94
	v_lshlrev_b32_e32 v114, 16, v95
	v_and_b32_e32 v115, 0xffff0000, v95
	v_mul_f32_e32 v120, v120, v56
	v_mul_f32_e32 v121, v121, v56
	v_mul_f32_e32 v122, v122, v56
	v_mul_f32_e32 v123, v123, v56
	v_mul_f32_e32 v112, v112, v56
	v_mul_f32_e32 v113, v113, v56
	v_mul_f32_e32 v114, v114, v56
	v_mul_f32_e32 v115, v115, v56
	v_pk_mul_f32 v[120:121], v[120:121], v[72:73]
	v_pk_mul_f32 v[122:123], v[122:123], v[74:75]
	v_pk_mul_f32 v[112:113], v[112:113], v[64:65]
	v_pk_mul_f32 v[114:115], v[114:115], v[66:67]
	v_cvt_pk_bf16_f32 v8, v120, v121
	v_cvt_pk_bf16_f32 v9, v122, v123
	v_cvt_pk_bf16_f32 v10, v112, v113
	v_cvt_pk_bf16_f32 v11, v114, v115
	global_store_dwordx4 v[0:1], v[8:11], off offset:256
	v_lshl_add_u64 v[0:1], v[0:1], 0, s[64:65]
	v_lshlrev_b32_e32 v120, 16, v116
	v_and_b32_e32 v121, 0xffff0000, v116
	v_lshlrev_b32_e32 v122, 16, v117
	v_and_b32_e32 v123, 0xffff0000, v117
	v_lshlrev_b32_e32 v112, 16, v118
	v_and_b32_e32 v113, 0xffff0000, v118
	v_lshlrev_b32_e32 v114, 16, v119
	v_and_b32_e32 v115, 0xffff0000, v119
	v_mul_f32_e32 v120, v120, v57
	v_mul_f32_e32 v121, v121, v57
	v_mul_f32_e32 v122, v122, v57
	v_mul_f32_e32 v123, v123, v57
	v_mul_f32_e32 v112, v112, v57
	v_mul_f32_e32 v113, v113, v57
	v_mul_f32_e32 v114, v114, v57
	v_mul_f32_e32 v115, v115, v57
	v_pk_mul_f32 v[120:121], v[120:121], v[88:89]
	v_pk_mul_f32 v[122:123], v[122:123], v[90:91]
	v_pk_mul_f32 v[112:113], v[112:113], v[80:81]
	v_pk_mul_f32 v[114:115], v[114:115], v[82:83]
	v_cvt_pk_bf16_f32 v8, v120, v121
	v_cvt_pk_bf16_f32 v9, v122, v123
	v_cvt_pk_bf16_f32 v10, v112, v113
	v_cvt_pk_bf16_f32 v11, v114, v115
	global_store_dwordx4 v[0:1], v[8:11], off
	v_lshlrev_b32_e32 v120, 16, v84
	v_and_b32_e32 v121, 0xffff0000, v84
	v_lshlrev_b32_e32 v122, 16, v85
	v_and_b32_e32 v123, 0xffff0000, v85
	v_lshlrev_b32_e32 v112, 16, v86
	v_and_b32_e32 v113, 0xffff0000, v86
	v_lshlrev_b32_e32 v114, 16, v87
	v_and_b32_e32 v115, 0xffff0000, v87
	v_mul_f32_e32 v120, v120, v57
	v_mul_f32_e32 v121, v121, v57
	v_mul_f32_e32 v122, v122, v57
	v_mul_f32_e32 v123, v123, v57
	v_mul_f32_e32 v112, v112, v57
	v_mul_f32_e32 v113, v113, v57
	v_mul_f32_e32 v114, v114, v57
	v_mul_f32_e32 v115, v115, v57
	v_pk_mul_f32 v[120:121], v[120:121], v[72:73]
	v_pk_mul_f32 v[122:123], v[122:123], v[74:75]
	v_pk_mul_f32 v[112:113], v[112:113], v[64:65]
	v_pk_mul_f32 v[114:115], v[114:115], v[66:67]
	v_cvt_pk_bf16_f32 v8, v120, v121
	v_cvt_pk_bf16_f32 v9, v122, v123
	v_cvt_pk_bf16_f32 v10, v112, v113
	v_cvt_pk_bf16_f32 v11, v114, v115
	global_store_dwordx4 v[0:1], v[8:11], off offset:256
	v_lshl_add_u64 v[0:1], v[0:1], 0, s[64:65]
	v_lshlrev_b32_e32 v120, 16, v108
	v_and_b32_e32 v121, 0xffff0000, v108
	v_lshlrev_b32_e32 v122, 16, v109
	v_and_b32_e32 v123, 0xffff0000, v109
	v_lshlrev_b32_e32 v112, 16, v110
	v_and_b32_e32 v113, 0xffff0000, v110
	v_lshlrev_b32_e32 v114, 16, v111
	v_and_b32_e32 v115, 0xffff0000, v111
	v_mul_f32_e32 v120, v120, v58
	v_mul_f32_e32 v121, v121, v58
	v_mul_f32_e32 v122, v122, v58
	v_mul_f32_e32 v123, v123, v58
	v_mul_f32_e32 v112, v112, v58
	v_mul_f32_e32 v113, v113, v58
	v_mul_f32_e32 v114, v114, v58
	v_mul_f32_e32 v115, v115, v58
	v_pk_mul_f32 v[120:121], v[120:121], v[88:89]
	v_pk_mul_f32 v[122:123], v[122:123], v[90:91]
	v_pk_mul_f32 v[112:113], v[112:113], v[80:81]
	v_pk_mul_f32 v[114:115], v[114:115], v[82:83]
	v_cvt_pk_bf16_f32 v8, v120, v121
	v_cvt_pk_bf16_f32 v9, v122, v123
	v_cvt_pk_bf16_f32 v10, v112, v113
	v_cvt_pk_bf16_f32 v11, v114, v115
	global_store_dwordx4 v[0:1], v[8:11], off
	v_lshlrev_b32_e32 v120, 16, v76
	v_and_b32_e32 v121, 0xffff0000, v76
	v_lshlrev_b32_e32 v122, 16, v77
	v_and_b32_e32 v123, 0xffff0000, v77
	v_lshlrev_b32_e32 v112, 16, v78
	v_and_b32_e32 v113, 0xffff0000, v78
	v_lshlrev_b32_e32 v114, 16, v79
	v_and_b32_e32 v115, 0xffff0000, v79
	v_mul_f32_e32 v120, v120, v58
	v_mul_f32_e32 v121, v121, v58
	v_mul_f32_e32 v122, v122, v58
	v_mul_f32_e32 v123, v123, v58
	v_mul_f32_e32 v112, v112, v58
; __device__ __forceinline__ unsigned pk2(float lo, float hi) { const f32x2 v = {lo, hi}; const hwbf16x2 b = __builtin_convertvector(v, hwbf16x2); return __builtin_bit_cast(unsigned, b); }
; template <bool OUT_F32, bool IN_BF16>
; __device__ __forceinline__ void phase_rmsnorm(const void* Xv, const float* gain, void* out) {
;     ...
;         for (int r = 0; r < RPT; ++r) { const int m = m0 + r * NGW; if (m >= NTOK) continue;
; #pragma unroll
;             for (int j = 0; j < 4; ++j) { const f32x4 y0 = v[r][j][0] * rs[r] * g[j][0], y1 = v[r][j][1] * rs[r] * g[j][1];
;                 if (OUT_F32) { float* o = (float*)out + (size_t)m * DM + 8 * lane + 512 * j; *(f32x4*)o = y0; *(f32x4*)(o + 4) = y1; }
;                 else { u32x4 w; w.x = pk2(y0.x, y0.y); w.y = pk2(y0.z, y0.w); w.z = pk2(y1.x, y1.y); w.w = pk2(y1.z, y1.w); *(u32x4*)((bf16_t*)out + (size_t)m * DM + 8 * lane + 512 * j) = w; } } }
	v_mul_f32_e32 v113, v113, v58
	v_mul_f32_e32 v114, v114, v58
	v_mul_f32_e32 v115, v115, v58
	v_pk_mul_f32 v[120:121], v[120:121], v[72:73]
	v_pk_mul_f32 v[122:123], v[122:123], v[74:75]
	v_pk_mul_f32 v[112:113], v[112:113], v[64:65]
	v_pk_mul_f32 v[114:115], v[114:115], v[66:67]
	v_cvt_pk_bf16_f32 v8, v120, v121
	v_cvt_pk_bf16_f32 v9, v122, v123
	v_cvt_pk_bf16_f32 v10, v112, v113
	v_cvt_pk_bf16_f32 v11, v114, v115
	global_store_dwordx4 v[0:1], v[8:11], off offset:256
	v_lshl_add_u64 v[0:1], v[0:1], 0, s[64:65]
	v_lshlrev_b32_e32 v120, 16, v100
	v_and_b32_e32 v121, 0xffff0000, v100
	v_lshlrev_b32_e32 v122, 16, v101
	v_and_b32_e32 v123, 0xffff0000, v101
	v_lshlrev_b32_e32 v112, 16, v102
	v_and_b32_e32 v113, 0xffff0000, v102
	v_lshlrev_b32_e32 v114, 16, v103
	v_and_b32_e32 v115, 0xffff0000, v103
	v_mul_f32_e32 v120, v120, v59
	v_mul_f32_e32 v121, v121, v59
	v_mul_f32_e32 v122, v122, v59
	v_mul_f32_e32 v123, v123, v59
	v_mul_f32_e32 v112, v112, v59
	v_mul_f32_e32 v113, v113, v59
	v_mul_f32_e32 v114, v114, v59
	v_mul_f32_e32 v115, v115, v59
	v_pk_mul_f32 v[120:121], v[120:121], v[88:89]
	v_pk_mul_f32 v[122:123], v[122:123], v[90:91]
	v_pk_mul_f32 v[112:113], v[112:113], v[80:81]
	v_pk_mul_f32 v[114:115], v[114:115], v[82:83]
	v_cvt_pk_bf16_f32 v8, v120, v121
	v_cvt_pk_bf16_f32 v9, v122, v123
	v_cvt_pk_bf16_f32 v10, v112, v113
	v_cvt_pk_bf16_f32 v11, v114, v115
	global_store_dwordx4 v[0:1], v[8:11], off
	v_lshlrev_b32_e32 v120, 16, v68
	v_and_b32_e32 v121, 0xffff0000, v68
	v_lshlrev_b32_e32 v122, 16, v69
	v_and_b32_e32 v123, 0xffff0000, v69
	v_lshlrev_b32_e32 v112, 16, v70
	v_and_b32_e32 v113, 0xffff0000, v70
	v_lshlrev_b32_e32 v114, 16, v71
	v_and_b32_e32 v115, 0xffff0000, v71
	v_mul_f32_e32 v120, v120, v59
	v_mul_f32_e32 v121, v121, v59
	v_mul_f32_e32 v122, v122, v59
	v_mul_f32_e32 v123, v123, v59
	v_mul_f32_e32 v112, v112, v59
	v_mul_f32_e32 v113, v113, v59
	v_mul_f32_e32 v114, v114, v59
	v_mul_f32_e32 v115, v115, v59
	v_pk_mul_f32 v[120:121], v[120:121], v[72:73]
	v_pk_mul_f32 v[122:123], v[122:123], v[74:75]
	v_pk_mul_f32 v[112:113], v[112:113], v[64:65]
	v_pk_mul_f32 v[114:115], v[114:115], v[66:67]
	v_cvt_pk_bf16_f32 v8, v120, v121
	v_cvt_pk_bf16_f32 v9, v122, v123
	v_cvt_pk_bf16_f32 v10, v112, v113
	v_cvt_pk_bf16_f32 v11, v114, v115
	global_store_dwordx4 v[0:1], v[8:11], off offset:256
	s_mov_b32 s64, 0x50000
	v_lshl_add_u64 v[0:1], v[0:1], 0, s[64:65]
	s_mov_b32 s64, 0x10000
	v_lshlrev_b32_e32 v120, 16, v60
	v_and_b32_e32 v121, 0xffff0000, v60
	v_lshlrev_b32_e32 v122, 16, v61
	v_and_b32_e32 v123, 0xffff0000, v61
	v_lshlrev_b32_e32 v112, 16, v62
	v_and_b32_e32 v113, 0xffff0000, v62
	v_lshlrev_b32_e32 v114, 16, v63
	v_and_b32_e32 v115, 0xffff0000, v63
	v_mul_f32_e32 v120, v120, v48
	v_mul_f32_e32 v121, v121, v48
	v_mul_f32_e32 v122, v122, v48
	v_mul_f32_e32 v123, v123, v48
	v_mul_f32_e32 v112, v112, v48
	v_mul_f32_e32 v113, v113, v48
	v_mul_f32_e32 v114, v114, v48
	v_mul_f32_e32 v115, v115, v48
	v_pk_mul_f32 v[120:121], v[120:121], v[88:89]
	v_pk_mul_f32 v[122:123], v[122:123], v[90:91]
	v_pk_mul_f32 v[112:113], v[112:113], v[80:81]
	v_pk_mul_f32 v[114:115], v[114:115], v[82:83]
	v_cvt_pk_bf16_f32 v8, v120, v121
	v_cvt_pk_bf16_f32 v9, v122, v123
	v_cvt_pk_bf16_f32 v10, v112, v113
	v_cvt_pk_bf16_f32 v11, v114, v115
	global_store_dwordx4 v[0:1], v[8:11], off
	v_lshlrev_b32_e32 v120, 16, v28
	v_and_b32_e32 v121, 0xffff0000, v28
	v_lshlrev_b32_e32 v122, 16, v29
	v_and_b32_e32 v123, 0xffff0000, v29
	v_lshlrev_b32_e32 v112, 16, v30
	v_and_b32_e32 v113, 0xffff0000, v30
	v_lshlrev_b32_e32 v114, 16, v31
	v_and_b32_e32 v115, 0xffff0000, v31
	v_mul_f32_e32 v120, v120, v48
	v_mul_f32_e32 v121, v121, v48
	v_mul_f32_e32 v122, v122, v48
	v_mul_f32_e32 v123, v123, v48
	v_mul_f32_e32 v112, v112, v48
	v_mul_f32_e32 v113, v113, v48
	v_mul_f32_e32 v114, v114, v48
	v_mul_f32_e32 v115, v115, v48
	v_pk_mul_f32 v[120:121], v[120:121], v[72:73]
	v_pk_mul_f32 v[122:123], v[122:123], v[74:75]
	v_pk_mul_f32 v[112:113], v[112:113], v[64:65]
	v_pk_mul_f32 v[114:115], v[114:115], v[66:67]
	v_cvt_pk_bf16_f32 v8, v120, v121
	v_cvt_pk_bf16_f32 v9, v122, v123
	v_cvt_pk_bf16_f32 v10, v112, v113
	v_cvt_pk_bf16_f32 v11, v114, v115
	global_store_dwordx4 v[0:1], v[8:11], off offset:256
	v_lshl_add_u64 v[0:1], v[0:1], 0, s[64:65]
	v_lshlrev_b32_e32 v120, 16, v52
	v_and_b32_e32 v121, 0xffff0000, v52
	v_lshlrev_b32_e32 v122, 16, v53
	v_and_b32_e32 v123, 0xffff0000, v53
	v_lshlrev_b32_e32 v112, 16, v54
	v_and_b32_e32 v113, 0xffff0000, v54
	v_lshlrev_b32_e32 v114, 16, v55
	v_and_b32_e32 v115, 0xffff0000, v55
	v_mul_f32_e32 v120, v120, v49
	v_mul_f32_e32 v121, v121, v49
	v_mul_f32_e32 v122, v122, v49
	v_mul_f32_e32 v123, v123, v49
	v_mul_f32_e32 v112, v112, v49
	v_mul_f32_e32 v113, v113, v49
	v_mul_f32_e32 v114, v114, v49
	v_mul_f32_e32 v115, v115, v49
	v_pk_mul_f32 v[120:121], v[120:121], v[88:89]
	v_pk_mul_f32 v[122:123], v[122:123], v[90:91]
	v_pk_mul_f32 v[112:113], v[112:113], v[80:81]
	v_pk_mul_f32 v[114:115], v[114:115], v[82:83]
	v_cvt_pk_bf16_f32 v8, v120, v121
	v_cvt_pk_bf16_f32 v9, v122, v123
	v_cvt_pk_bf16_f32 v10, v112, v113
	v_cvt_pk_bf16_f32 v11, v114, v115
	global_store_dwordx4 v[0:1], v[8:11], off
	v_lshlrev_b32_e32 v120, 16, v20
	v_and_b32_e32 v121, 0xffff0000, v20
	v_lshlrev_b32_e32 v122, 16, v21
	v_and_b32_e32 v123, 0xffff0000, v21
	v_lshlrev_b32_e32 v112, 16, v22
	v_and_b32_e32 v113, 0xffff0000, v22
	v_lshlrev_b32_e32 v114, 16, v23
	v_and_b32_e32 v115, 0xffff0000, v23
	v_mul_f32_e32 v120, v120, v49
	v_mul_f32_e32 v121, v121, v49
	v_mul_f32_e32 v122, v122, v49
	v_mul_f32_e32 v123, v123, v49
	v_mul_f32_e32 v112, v112, v49
	v_mul_f32_e32 v113, v113, v49
; __device__ __forceinline__ unsigned pk2(float lo, float hi) { const f32x2 v = {lo, hi}; const hwbf16x2 b = __builtin_convertvector(v, hwbf16x2); return __builtin_bit_cast(unsigned, b); }
; template <bool OUT_F32, bool IN_BF16>
; __device__ __forceinline__ void phase_rmsnorm(const void* Xv, const float* gain, void* out) {
;     ...
;         for (int r = 0; r < RPT; ++r) { const int m = m0 + r * NGW; if (m >= NTOK) continue;
; #pragma unroll
;             for (int j = 0; j < 4; ++j) { const f32x4 y0 = v[r][j][0] * rs[r] * g[j][0], y1 = v[r][j][1] * rs[r] * g[j][1];
;                 if (OUT_F32) { float* o = (float*)out + (size_t)m * DM + 8 * lane + 512 * j; *(f32x4*)o = y0; *(f32x4*)(o + 4) = y1; }
;                 else { u32x4 w; w.x = pk2(y0.x, y0.y); w.y = pk2(y0.z, y0.w); w.z = pk2(y1.x, y1.y); w.w = pk2(y1.z, y1.w); *(u32x4*)((bf16_t*)out + (size_t)m * DM + 8 * lane + 512 * j) = w; } } }
; __global__ void __launch_bounds__(NTHREADS) fwd_megakernel(Params p) {
;     ...
;         else if (ph == NPHASE - 1) phase_rmsnorm<true, true>(XB, p.final_norm, p.out);
	v_mul_f32_e32 v114, v114, v49
	v_mul_f32_e32 v115, v115, v49
	v_pk_mul_f32 v[120:121], v[120:121], v[72:73]
	v_pk_mul_f32 v[122:123], v[122:123], v[74:75]
	v_pk_mul_f32 v[112:113], v[112:113], v[64:65]
	v_pk_mul_f32 v[114:115], v[114:115], v[66:67]
	v_cvt_pk_bf16_f32 v8, v120, v121
	v_cvt_pk_bf16_f32 v9, v122, v123
	v_cvt_pk_bf16_f32 v10, v112, v113
	v_cvt_pk_bf16_f32 v11, v114, v115
	global_store_dwordx4 v[0:1], v[8:11], off offset:256
	v_lshl_add_u64 v[0:1], v[0:1], 0, s[64:65]
	v_lshlrev_b32_e32 v120, 16, v44
	v_and_b32_e32 v121, 0xffff0000, v44
	v_lshlrev_b32_e32 v122, 16, v45
	v_and_b32_e32 v123, 0xffff0000, v45
	v_lshlrev_b32_e32 v112, 16, v46
	v_and_b32_e32 v113, 0xffff0000, v46
	v_lshlrev_b32_e32 v114, 16, v47
	v_and_b32_e32 v115, 0xffff0000, v47
	v_mul_f32_e32 v120, v120, v50
	v_mul_f32_e32 v121, v121, v50
	v_mul_f32_e32 v122, v122, v50
	v_mul_f32_e32 v123, v123, v50
	v_mul_f32_e32 v112, v112, v50
	v_mul_f32_e32 v113, v113, v50
	v_mul_f32_e32 v114, v114, v50
	v_mul_f32_e32 v115, v115, v50
	v_pk_mul_f32 v[120:121], v[120:121], v[88:89]
	v_pk_mul_f32 v[122:123], v[122:123], v[90:91]
	v_pk_mul_f32 v[112:113], v[112:113], v[80:81]
	v_pk_mul_f32 v[114:115], v[114:115], v[82:83]
	v_cvt_pk_bf16_f32 v8, v120, v121
	v_cvt_pk_bf16_f32 v9, v122, v123
	v_cvt_pk_bf16_f32 v10, v112, v113
	v_cvt_pk_bf16_f32 v11, v114, v115
	global_store_dwordx4 v[0:1], v[8:11], off
	v_lshlrev_b32_e32 v120, 16, v12
	v_and_b32_e32 v121, 0xffff0000, v12
	v_lshlrev_b32_e32 v122, 16, v13
	v_and_b32_e32 v123, 0xffff0000, v13
	v_lshlrev_b32_e32 v112, 16, v14
	v_and_b32_e32 v113, 0xffff0000, v14
	v_lshlrev_b32_e32 v114, 16, v15
	v_and_b32_e32 v115, 0xffff0000, v15
	v_mul_f32_e32 v120, v120, v50
	v_mul_f32_e32 v121, v121, v50
	v_mul_f32_e32 v122, v122, v50
	v_mul_f32_e32 v123, v123, v50
	v_mul_f32_e32 v112, v112, v50
	v_mul_f32_e32 v113, v113, v50
	v_mul_f32_e32 v114, v114, v50
	v_mul_f32_e32 v115, v115, v50
	v_pk_mul_f32 v[120:121], v[120:121], v[72:73]
	v_pk_mul_f32 v[122:123], v[122:123], v[74:75]
	v_pk_mul_f32 v[112:113], v[112:113], v[64:65]
	v_pk_mul_f32 v[114:115], v[114:115], v[66:67]
	v_cvt_pk_bf16_f32 v8, v120, v121
	v_cvt_pk_bf16_f32 v9, v122, v123
	v_cvt_pk_bf16_f32 v10, v112, v113
	v_cvt_pk_bf16_f32 v11, v114, v115
	global_store_dwordx4 v[0:1], v[8:11], off offset:256
	v_lshl_add_u64 v[0:1], v[0:1], 0, s[64:65]
	v_lshlrev_b32_e32 v120, 16, v36
	v_and_b32_e32 v121, 0xffff0000, v36
	v_lshlrev_b32_e32 v122, 16, v37
	v_and_b32_e32 v123, 0xffff0000, v37
	v_lshlrev_b32_e32 v112, 16, v38
	v_and_b32_e32 v113, 0xffff0000, v38
	v_lshlrev_b32_e32 v114, 16, v39
	v_and_b32_e32 v115, 0xffff0000, v39
	v_mul_f32_e32 v120, v120, v51
	v_mul_f32_e32 v121, v121, v51
	v_mul_f32_e32 v122, v122, v51
	v_mul_f32_e32 v123, v123, v51
	v_mul_f32_e32 v112, v112, v51
	v_mul_f32_e32 v113, v113, v51
	v_mul_f32_e32 v114, v114, v51
	v_mul_f32_e32 v115, v115, v51
	v_pk_mul_f32 v[120:121], v[120:121], v[88:89]
	v_pk_mul_f32 v[122:123], v[122:123], v[90:91]
	v_pk_mul_f32 v[112:113], v[112:113], v[80:81]
	v_pk_mul_f32 v[114:115], v[114:115], v[82:83]
	v_cvt_pk_bf16_f32 v8, v120, v121
	v_cvt_pk_bf16_f32 v9, v122, v123
	v_cvt_pk_bf16_f32 v10, v112, v113
	v_cvt_pk_bf16_f32 v11, v114, v115
	global_store_dwordx4 v[0:1], v[8:11], off
	v_lshlrev_b32_e32 v120, 16, v4
	v_and_b32_e32 v121, 0xffff0000, v4
	v_lshlrev_b32_e32 v122, 16, v5
	v_and_b32_e32 v123, 0xffff0000, v5
	v_lshlrev_b32_e32 v112, 16, v6
	v_and_b32_e32 v113, 0xffff0000, v6
	v_lshlrev_b32_e32 v114, 16, v7
	v_and_b32_e32 v115, 0xffff0000, v7
	v_mul_f32_e32 v120, v120, v51
	v_mul_f32_e32 v121, v121, v51
	v_mul_f32_e32 v122, v122, v51
	v_mul_f32_e32 v123, v123, v51
	v_mul_f32_e32 v112, v112, v51
	v_mul_f32_e32 v113, v113, v51
	v_mul_f32_e32 v114, v114, v51
	v_mul_f32_e32 v115, v115, v51
	v_pk_mul_f32 v[120:121], v[120:121], v[72:73]
	v_pk_mul_f32 v[122:123], v[122:123], v[74:75]
	v_pk_mul_f32 v[112:113], v[112:113], v[64:65]
	v_pk_mul_f32 v[114:115], v[114:115], v[66:67]
	v_cvt_pk_bf16_f32 v8, v120, v121
	v_cvt_pk_bf16_f32 v9, v122, v123
	v_cvt_pk_bf16_f32 v10, v112, v113
	v_cvt_pk_bf16_f32 v11, v114, v115
	global_store_dwordx4 v[0:1], v[8:11], off offset:256
	s_branch .Lln_end
.Lln_out_final:
	s_add_u32 s64, s88, 0x1b900000
	s_addc_u32 s65, s89, 0
	v_mov_b32_e32 v16, s64
	v_mov_b32_e32 v17, s65
	v_sub_co_u32_e32 v24, vcc, v174, v16
	s_nop 1
	v_subb_co_u32_e32 v25, vcc, v175, v17, vcc
	v_readlane_b32 s64, v255, 20
	v_readlane_b32 s65, v255, 21
	s_nop 0
	v_lshl_add_u64 v[0:1], v[24:25], 1, s[64:65]
	s_mov_b32 s64, 0x20000
	s_mov_b32 s65, 0
	s_waitcnt vmcnt(0) lgkmcnt(0)
; template <bool OUT_F32, bool IN_BF16>
; __device__ __forceinline__ void phase_rmsnorm(const void* Xv, const float* gain, void* out) {
;     ...
;         for (int r = 0; r < RPT; ++r) { const int m = m0 + r * NGW; if (m >= NTOK) continue;
; #pragma unroll
;             for (int j = 0; j < 4; ++j) { const f32x4 y0 = v[r][j][0] * rs[r] * g[j][0], y1 = v[r][j][1] * rs[r] * g[j][1];
;                 if (OUT_F32) { float* o = (float*)out + (size_t)m * DM + 8 * lane + 512 * j; *(f32x4*)o = y0; *(f32x4*)(o + 4) = y1; }
	v_lshlrev_b32_e32 v120, 16, v124
	v_and_b32_e32 v121, 0xffff0000, v124
	v_lshlrev_b32_e32 v122, 16, v125
	v_and_b32_e32 v123, 0xffff0000, v125
	v_lshlrev_b32_e32 v112, 16, v126
	v_and_b32_e32 v113, 0xffff0000, v126
	v_lshlrev_b32_e32 v114, 16, v127
	v_and_b32_e32 v115, 0xffff0000, v127
	v_mul_f32_e32 v120, v120, v56
	v_mul_f32_e32 v121, v121, v56
	v_mul_f32_e32 v122, v122, v56
	v_mul_f32_e32 v123, v123, v56
	v_mul_f32_e32 v112, v112, v56
	v_mul_f32_e32 v113, v113, v56
	v_mul_f32_e32 v114, v114, v56
	v_mul_f32_e32 v115, v115, v56
	v_pk_mul_f32 v[120:121], v[120:121], v[88:89]
	v_pk_mul_f32 v[122:123], v[122:123], v[90:91]
	v_pk_mul_f32 v[112:113], v[112:113], v[80:81]
	v_pk_mul_f32 v[114:115], v[114:115], v[82:83]
	s_nop 0
	global_store_dwordx4 v[0:1], v[120:123], off
	global_store_dwordx4 v[0:1], v[112:115], off offset:16
	s_nop 1
	v_lshlrev_b32_e32 v120, 16, v92
	v_and_b32_e32 v121, 0xffff0000, v92
	v_lshlrev_b32_e32 v122, 16, v93
	v_and_b32_e32 v123, 0xffff0000, v93
	v_lshlrev_b32_e32 v112, 16, v94
	v_and_b32_e32 v113, 0xffff0000, v94
	v_lshlrev_b32_e32 v114, 16, v95
	v_and_b32_e32 v115, 0xffff0000, v95
	v_mul_f32_e32 v120, v120, v56
	v_mul_f32_e32 v121, v121, v56
	v_mul_f32_e32 v122, v122, v56
	v_mul_f32_e32 v123, v123, v56
	v_mul_f32_e32 v112, v112, v56
	v_mul_f32_e32 v113, v113, v56
	v_mul_f32_e32 v114, v114, v56
	v_mul_f32_e32 v115, v115, v56
	v_pk_mul_f32 v[120:121], v[120:121], v[72:73]
	v_pk_mul_f32 v[122:123], v[122:123], v[74:75]
	v_pk_mul_f32 v[112:113], v[112:113], v[64:65]
	v_pk_mul_f32 v[114:115], v[114:115], v[66:67]
	s_nop 0
	global_store_dwordx4 v[0:1], v[120:123], off offset:512
	global_store_dwordx4 v[0:1], v[112:115], off offset:528
	s_nop 1
	v_lshl_add_u64 v[0:1], v[0:1], 0, s[64:65]
	v_lshlrev_b32_e32 v120, 16, v116
	v_and_b32_e32 v121, 0xffff0000, v116
	v_lshlrev_b32_e32 v122, 16, v117
	v_and_b32_e32 v123, 0xffff0000, v117
	v_lshlrev_b32_e32 v112, 16, v118
	v_and_b32_e32 v113, 0xffff0000, v118
	v_lshlrev_b32_e32 v114, 16, v119
	v_and_b32_e32 v115, 0xffff0000, v119
	v_mul_f32_e32 v120, v120, v57
	v_mul_f32_e32 v121, v121, v57
	v_mul_f32_e32 v122, v122, v57
	v_mul_f32_e32 v123, v123, v57
	v_mul_f32_e32 v112, v112, v57
	v_mul_f32_e32 v113, v113, v57
	v_mul_f32_e32 v114, v114, v57
	v_mul_f32_e32 v115, v115, v57
	v_pk_mul_f32 v[120:121], v[120:121], v[88:89]
	v_pk_mul_f32 v[122:123], v[122:123], v[90:91]
	v_pk_mul_f32 v[112:113], v[112:113], v[80:81]
	v_pk_mul_f32 v[114:115], v[114:115], v[82:83]
	s_nop 0
	global_store_dwordx4 v[0:1], v[120:123], off
	global_store_dwordx4 v[0:1], v[112:115], off offset:16
	s_nop 1
	v_lshlrev_b32_e32 v120, 16, v84
	v_and_b32_e32 v121, 0xffff0000, v84
	v_lshlrev_b32_e32 v122, 16, v85
	v_and_b32_e32 v123, 0xffff0000, v85
	v_lshlrev_b32_e32 v112, 16, v86
	v_and_b32_e32 v113, 0xffff0000, v86
	v_lshlrev_b32_e32 v114, 16, v87
	v_and_b32_e32 v115, 0xffff0000, v87
	v_mul_f32_e32 v120, v120, v57
	v_mul_f32_e32 v121, v121, v57
	v_mul_f32_e32 v122, v122, v57
	v_mul_f32_e32 v123, v123, v57
	v_mul_f32_e32 v112, v112, v57
	v_mul_f32_e32 v113, v113, v57
	v_mul_f32_e32 v114, v114, v57
	v_mul_f32_e32 v115, v115, v57
	v_pk_mul_f32 v[120:121], v[120:121], v[72:73]
	v_pk_mul_f32 v[122:123], v[122:123], v[74:75]
	v_pk_mul_f32 v[112:113], v[112:113], v[64:65]
	v_pk_mul_f32 v[114:115], v[114:115], v[66:67]
	s_nop 0
	global_store_dwordx4 v[0:1], v[120:123], off offset:512
	global_store_dwordx4 v[0:1], v[112:115], off offset:528
	s_nop 1
	v_lshl_add_u64 v[0:1], v[0:1], 0, s[64:65]
	v_lshlrev_b32_e32 v120, 16, v108
	v_and_b32_e32 v121, 0xffff0000, v108
	v_lshlrev_b32_e32 v122, 16, v109
	v_and_b32_e32 v123, 0xffff0000, v109
	v_lshlrev_b32_e32 v112, 16, v110
	v_and_b32_e32 v113, 0xffff0000, v110
	v_lshlrev_b32_e32 v114, 16, v111
	v_and_b32_e32 v115, 0xffff0000, v111
	v_mul_f32_e32 v120, v120, v58
	v_mul_f32_e32 v121, v121, v58
	v_mul_f32_e32 v122, v122, v58
	v_mul_f32_e32 v123, v123, v58
	v_mul_f32_e32 v112, v112, v58
	v_mul_f32_e32 v113, v113, v58
	v_mul_f32_e32 v114, v114, v58
	v_mul_f32_e32 v115, v115, v58
	v_pk_mul_f32 v[120:121], v[120:121], v[88:89]
	v_pk_mul_f32 v[122:123], v[122:123], v[90:91]
	v_pk_mul_f32 v[112:113], v[112:113], v[80:81]
	v_pk_mul_f32 v[114:115], v[114:115], v[82:83]
	s_nop 0
	global_store_dwordx4 v[0:1], v[120:123], off
	global_store_dwordx4 v[0:1], v[112:115], off offset:16
	s_nop 1
	v_lshlrev_b32_e32 v120, 16, v76
	v_and_b32_e32 v121, 0xffff0000, v76
	v_lshlrev_b32_e32 v122, 16, v77
	v_and_b32_e32 v123, 0xffff0000, v77
	v_lshlrev_b32_e32 v112, 16, v78
	v_and_b32_e32 v113, 0xffff0000, v78
	v_lshlrev_b32_e32 v114, 16, v79
	v_and_b32_e32 v115, 0xffff0000, v79
	v_mul_f32_e32 v120, v120, v58
	v_mul_f32_e32 v121, v121, v58
	v_mul_f32_e32 v122, v122, v58
	v_mul_f32_e32 v123, v123, v58
	v_mul_f32_e32 v112, v112, v58
	v_mul_f32_e32 v113, v113, v58
	v_mul_f32_e32 v114, v114, v58
	v_mul_f32_e32 v115, v115, v58
	v_pk_mul_f32 v[120:121], v[120:121], v[72:73]
	v_pk_mul_f32 v[122:123], v[122:123], v[74:75]
	v_pk_mul_f32 v[112:113], v[112:113], v[64:65]
	v_pk_mul_f32 v[114:115], v[114:115], v[66:67]
	s_nop 0
	global_store_dwordx4 v[0:1], v[120:123], off offset:512
	global_store_dwordx4 v[0:1], v[112:115], off offset:528
	s_nop 1
	v_lshl_add_u64 v[0:1], v[0:1], 0, s[64:65]
	v_lshlrev_b32_e32 v120, 16, v100
	v_and_b32_e32 v121, 0xffff0000, v100
	v_lshlrev_b32_e32 v122, 16, v101
	v_and_b32_e32 v123, 0xffff0000, v101
	v_lshlrev_b32_e32 v112, 16, v102
	v_and_b32_e32 v113, 0xffff0000, v102
	v_lshlrev_b32_e32 v114, 16, v103
	v_and_b32_e32 v115, 0xffff0000, v103
	v_mul_f32_e32 v120, v120, v59
	v_mul_f32_e32 v121, v121, v59
	v_mul_f32_e32 v122, v122, v59
	v_mul_f32_e32 v123, v123, v59
	v_mul_f32_e32 v112, v112, v59
; template <bool OUT_F32, bool IN_BF16>
; __device__ __forceinline__ void phase_rmsnorm(const void* Xv, const float* gain, void* out) {
;     ...
;         for (int r = 0; r < RPT; ++r) { const int m = m0 + r * NGW; if (m >= NTOK) continue;
; #pragma unroll
;             for (int j = 0; j < 4; ++j) { const f32x4 y0 = v[r][j][0] * rs[r] * g[j][0], y1 = v[r][j][1] * rs[r] * g[j][1];
;                 if (OUT_F32) { float* o = (float*)out + (size_t)m * DM + 8 * lane + 512 * j; *(f32x4*)o = y0; *(f32x4*)(o + 4) = y1; }
	v_mul_f32_e32 v113, v113, v59
	v_mul_f32_e32 v114, v114, v59
	v_mul_f32_e32 v115, v115, v59
	v_pk_mul_f32 v[120:121], v[120:121], v[88:89]
	v_pk_mul_f32 v[122:123], v[122:123], v[90:91]
	v_pk_mul_f32 v[112:113], v[112:113], v[80:81]
	v_pk_mul_f32 v[114:115], v[114:115], v[82:83]
	s_nop 0
	global_store_dwordx4 v[0:1], v[120:123], off
	global_store_dwordx4 v[0:1], v[112:115], off offset:16
	s_nop 1
	v_lshlrev_b32_e32 v120, 16, v68
	v_and_b32_e32 v121, 0xffff0000, v68
	v_lshlrev_b32_e32 v122, 16, v69
	v_and_b32_e32 v123, 0xffff0000, v69
	v_lshlrev_b32_e32 v112, 16, v70
	v_and_b32_e32 v113, 0xffff0000, v70
	v_lshlrev_b32_e32 v114, 16, v71
	v_and_b32_e32 v115, 0xffff0000, v71
	v_mul_f32_e32 v120, v120, v59
	v_mul_f32_e32 v121, v121, v59
	v_mul_f32_e32 v122, v122, v59
	v_mul_f32_e32 v123, v123, v59
	v_mul_f32_e32 v112, v112, v59
	v_mul_f32_e32 v113, v113, v59
	v_mul_f32_e32 v114, v114, v59
	v_mul_f32_e32 v115, v115, v59
	v_pk_mul_f32 v[120:121], v[120:121], v[72:73]
	v_pk_mul_f32 v[122:123], v[122:123], v[74:75]
	v_pk_mul_f32 v[112:113], v[112:113], v[64:65]
	v_pk_mul_f32 v[114:115], v[114:115], v[66:67]
	s_nop 0
	global_store_dwordx4 v[0:1], v[120:123], off offset:512
	global_store_dwordx4 v[0:1], v[112:115], off offset:528
	s_nop 1
	s_mov_b32 s64, 0xa0000
	v_lshl_add_u64 v[0:1], v[0:1], 0, s[64:65]
	s_mov_b32 s64, 0x20000
	v_lshlrev_b32_e32 v120, 16, v60
	v_and_b32_e32 v121, 0xffff0000, v60
	v_lshlrev_b32_e32 v122, 16, v61
	v_and_b32_e32 v123, 0xffff0000, v61
	v_lshlrev_b32_e32 v112, 16, v62
	v_and_b32_e32 v113, 0xffff0000, v62
	v_lshlrev_b32_e32 v114, 16, v63
	v_and_b32_e32 v115, 0xffff0000, v63
	v_mul_f32_e32 v120, v120, v48
	v_mul_f32_e32 v121, v121, v48
	v_mul_f32_e32 v122, v122, v48
	v_mul_f32_e32 v123, v123, v48
	v_mul_f32_e32 v112, v112, v48
	v_mul_f32_e32 v113, v113, v48
	v_mul_f32_e32 v114, v114, v48
	v_mul_f32_e32 v115, v115, v48
	v_pk_mul_f32 v[120:121], v[120:121], v[88:89]
	v_pk_mul_f32 v[122:123], v[122:123], v[90:91]
	v_pk_mul_f32 v[112:113], v[112:113], v[80:81]
	v_pk_mul_f32 v[114:115], v[114:115], v[82:83]
	s_nop 0
	global_store_dwordx4 v[0:1], v[120:123], off
	global_store_dwordx4 v[0:1], v[112:115], off offset:16
	s_nop 1
	v_lshlrev_b32_e32 v120, 16, v28
	v_and_b32_e32 v121, 0xffff0000, v28
	v_lshlrev_b32_e32 v122, 16, v29
	v_and_b32_e32 v123, 0xffff0000, v29
	v_lshlrev_b32_e32 v112, 16, v30
	v_and_b32_e32 v113, 0xffff0000, v30
	v_lshlrev_b32_e32 v114, 16, v31
	v_and_b32_e32 v115, 0xffff0000, v31
	v_mul_f32_e32 v120, v120, v48
	v_mul_f32_e32 v121, v121, v48
	v_mul_f32_e32 v122, v122, v48
	v_mul_f32_e32 v123, v123, v48
	v_mul_f32_e32 v112, v112, v48
	v_mul_f32_e32 v113, v113, v48
	v_mul_f32_e32 v114, v114, v48
	v_mul_f32_e32 v115, v115, v48
	v_pk_mul_f32 v[120:121], v[120:121], v[72:73]
	v_pk_mul_f32 v[122:123], v[122:123], v[74:75]
	v_pk_mul_f32 v[112:113], v[112:113], v[64:65]
	v_pk_mul_f32 v[114:115], v[114:115], v[66:67]
	s_nop 0
	global_store_dwordx4 v[0:1], v[120:123], off offset:512
	global_store_dwordx4 v[0:1], v[112:115], off offset:528
	s_nop 1
	v_lshl_add_u64 v[0:1], v[0:1], 0, s[64:65]
	v_lshlrev_b32_e32 v120, 16, v52
	v_and_b32_e32 v121, 0xffff0000, v52
	v_lshlrev_b32_e32 v122, 16, v53
	v_and_b32_e32 v123, 0xffff0000, v53
	v_lshlrev_b32_e32 v112, 16, v54
	v_and_b32_e32 v113, 0xffff0000, v54
	v_lshlrev_b32_e32 v114, 16, v55
	v_and_b32_e32 v115, 0xffff0000, v55
	v_mul_f32_e32 v120, v120, v49
	v_mul_f32_e32 v121, v121, v49
	v_mul_f32_e32 v122, v122, v49
	v_mul_f32_e32 v123, v123, v49
	v_mul_f32_e32 v112, v112, v49
	v_mul_f32_e32 v113, v113, v49
	v_mul_f32_e32 v114, v114, v49
	v_mul_f32_e32 v115, v115, v49
	v_pk_mul_f32 v[120:121], v[120:121], v[88:89]
	v_pk_mul_f32 v[122:123], v[122:123], v[90:91]
	v_pk_mul_f32 v[112:113], v[112:113], v[80:81]
	v_pk_mul_f32 v[114:115], v[114:115], v[82:83]
	s_nop 0
	global_store_dwordx4 v[0:1], v[120:123], off
	global_store_dwordx4 v[0:1], v[112:115], off offset:16
	s_nop 1
	v_lshlrev_b32_e32 v120, 16, v20
	v_and_b32_e32 v121, 0xffff0000, v20
	v_lshlrev_b32_e32 v122, 16, v21
	v_and_b32_e32 v123, 0xffff0000, v21
	v_lshlrev_b32_e32 v112, 16, v22
	v_and_b32_e32 v113, 0xffff0000, v22
; template <bool OUT_F32, bool IN_BF16>
; __device__ __forceinline__ void phase_rmsnorm(const void* Xv, const float* gain, void* out) {
;     ...
;         for (int r = 0; r < RPT; ++r) { const int m = m0 + r * NGW; if (m >= NTOK) continue;
; #pragma unroll
;             for (int j = 0; j < 4; ++j) { const f32x4 y0 = v[r][j][0] * rs[r] * g[j][0], y1 = v[r][j][1] * rs[r] * g[j][1];
;                 if (OUT_F32) { float* o = (float*)out + (size_t)m * DM + 8 * lane + 512 * j; *(f32x4*)o = y0; *(f32x4*)(o + 4) = y1; }
	v_lshlrev_b32_e32 v114, 16, v23
	v_and_b32_e32 v115, 0xffff0000, v23
	v_mul_f32_e32 v120, v120, v49
	v_mul_f32_e32 v121, v121, v49
	v_mul_f32_e32 v122, v122, v49
	v_mul_f32_e32 v123, v123, v49
	v_mul_f32_e32 v112, v112, v49
	v_mul_f32_e32 v113, v113, v49
	v_mul_f32_e32 v114, v114, v49
	v_mul_f32_e32 v115, v115, v49
	v_pk_mul_f32 v[120:121], v[120:121], v[72:73]
	v_pk_mul_f32 v[122:123], v[122:123], v[74:75]
	v_pk_mul_f32 v[112:113], v[112:113], v[64:65]
	v_pk_mul_f32 v[114:115], v[114:115], v[66:67]
	s_nop 0
	global_store_dwordx4 v[0:1], v[120:123], off offset:512
	global_store_dwordx4 v[0:1], v[112:115], off offset:528
	s_nop 1
	v_lshl_add_u64 v[0:1], v[0:1], 0, s[64:65]
	v_lshlrev_b32_e32 v120, 16, v44
	v_and_b32_e32 v121, 0xffff0000, v44
	v_lshlrev_b32_e32 v122, 16, v45
	v_and_b32_e32 v123, 0xffff0000, v45
	v_lshlrev_b32_e32 v112, 16, v46
	v_and_b32_e32 v113, 0xffff0000, v46
	v_lshlrev_b32_e32 v114, 16, v47
	v_and_b32_e32 v115, 0xffff0000, v47
	v_mul_f32_e32 v120, v120, v50
	v_mul_f32_e32 v121, v121, v50
	v_mul_f32_e32 v122, v122, v50
	v_mul_f32_e32 v123, v123, v50
	v_mul_f32_e32 v112, v112, v50
	v_mul_f32_e32 v113, v113, v50
	v_mul_f32_e32 v114, v114, v50
	v_mul_f32_e32 v115, v115, v50
	v_pk_mul_f32 v[120:121], v[120:121], v[88:89]
	v_pk_mul_f32 v[122:123], v[122:123], v[90:91]
	v_pk_mul_f32 v[112:113], v[112:113], v[80:81]
	v_pk_mul_f32 v[114:115], v[114:115], v[82:83]
	s_nop 0
	global_store_dwordx4 v[0:1], v[120:123], off
	global_store_dwordx4 v[0:1], v[112:115], off offset:16
	s_nop 1
	v_lshlrev_b32_e32 v120, 16, v12
	v_and_b32_e32 v121, 0xffff0000, v12
	v_lshlrev_b32_e32 v122, 16, v13
	v_and_b32_e32 v123, 0xffff0000, v13
	v_lshlrev_b32_e32 v112, 16, v14
	v_and_b32_e32 v113, 0xffff0000, v14
	v_lshlrev_b32_e32 v114, 16, v15
	v_and_b32_e32 v115, 0xffff0000, v15
	v_mul_f32_e32 v120, v120, v50
	v_mul_f32_e32 v121, v121, v50
	v_mul_f32_e32 v122, v122, v50
	v_mul_f32_e32 v123, v123, v50
	v_mul_f32_e32 v112, v112, v50
	v_mul_f32_e32 v113, v113, v50
	v_mul_f32_e32 v114, v114, v50
	v_mul_f32_e32 v115, v115, v50
	v_pk_mul_f32 v[120:121], v[120:121], v[72:73]
	v_pk_mul_f32 v[122:123], v[122:123], v[74:75]
	v_pk_mul_f32 v[112:113], v[112:113], v[64:65]
	v_pk_mul_f32 v[114:115], v[114:115], v[66:67]
	s_nop 0
	global_store_dwordx4 v[0:1], v[120:123], off offset:512
	global_store_dwordx4 v[0:1], v[112:115], off offset:528
	s_nop 1
	v_lshl_add_u64 v[0:1], v[0:1], 0, s[64:65]
	v_lshlrev_b32_e32 v120, 16, v36
	v_and_b32_e32 v121, 0xffff0000, v36
	v_lshlrev_b32_e32 v122, 16, v37
	v_and_b32_e32 v123, 0xffff0000, v37
	v_lshlrev_b32_e32 v112, 16, v38
	v_and_b32_e32 v113, 0xffff0000, v38
	v_lshlrev_b32_e32 v114, 16, v39
	v_and_b32_e32 v115, 0xffff0000, v39
	v_mul_f32_e32 v120, v120, v51
	v_mul_f32_e32 v121, v121, v51
	v_mul_f32_e32 v122, v122, v51
	v_mul_f32_e32 v123, v123, v51
	v_mul_f32_e32 v112, v112, v51
	v_mul_f32_e32 v113, v113, v51
	v_mul_f32_e32 v114, v114, v51
	v_mul_f32_e32 v115, v115, v51
	v_pk_mul_f32 v[120:121], v[120:121], v[88:89]
	v_pk_mul_f32 v[122:123], v[122:123], v[90:91]
	v_pk_mul_f32 v[112:113], v[112:113], v[80:81]
	v_pk_mul_f32 v[114:115], v[114:115], v[82:83]
	s_nop 0
	global_store_dwordx4 v[0:1], v[120:123], off
	global_store_dwordx4 v[0:1], v[112:115], off offset:16
	s_nop 1
	v_lshlrev_b32_e32 v120, 16, v4
	v_and_b32_e32 v121, 0xffff0000, v4
	v_lshlrev_b32_e32 v122, 16, v5
	v_and_b32_e32 v123, 0xffff0000, v5
	v_lshlrev_b32_e32 v112, 16, v6
	v_and_b32_e32 v113, 0xffff0000, v6
	v_lshlrev_b32_e32 v114, 16, v7
	v_and_b32_e32 v115, 0xffff0000, v7
	v_mul_f32_e32 v120, v120, v51
	v_mul_f32_e32 v121, v121, v51
	v_mul_f32_e32 v122, v122, v51
	v_mul_f32_e32 v123, v123, v51
	v_mul_f32_e32 v112, v112, v51
	v_mul_f32_e32 v113, v113, v51
	v_mul_f32_e32 v114, v114, v51
	v_mul_f32_e32 v115, v115, v51
	v_pk_mul_f32 v[120:121], v[120:121], v[72:73]
	v_pk_mul_f32 v[122:123], v[122:123], v[74:75]
	v_pk_mul_f32 v[112:113], v[112:113], v[64:65]
	v_pk_mul_f32 v[114:115], v[114:115], v[66:67]
	s_nop 0
	global_store_dwordx4 v[0:1], v[120:123], off offset:512
	global_store_dwordx4 v[0:1], v[112:115], off offset:528
	s_nop 1

; __global__ void __launch_bounds__(NTHREADS) fwd_megakernel(Params p) {
;     ...
;     for (int ph = p.ph_lo; ph < p.ph_hi; ++ph) {
;         bool need_bar = true;
;         if (ph == 0) { phase_prep(p, lds); phase_rmsnorm<false, false>(p.x, p.norm_mix, ws + WS_XN); }
;         else if (ph == NPHASE - 1) phase_rmsnorm<true, true>(XB, p.final_norm, p.out);
.Lln_latch:
	s_add_i32 s90, s90, 1
	s_cmp_eq_u32 s90, 33
	s_cbranch_scc1 .Lln_latch_skip
	s_mov_b32 s100, 0x42424240
	s_bitcmp1_b32 s100, s90
	s_cbranch_scc0 .Lln_latch_ret
.Lln_latch_skip:
	s_add_i32 s90, s90, 1
	s_branch .Lln_latch_ret
